# w_in epilogue: branch-free path also for the indexer-k + head-weight column tile of prompt rows (exec-masked dwordx4 stores)
# baseline (speedup 1.0000x reference)
.Lwin_ki:
	s_cmp_gt_u32 s14, 255
	s_cbranch_scc1 .Lwin_slow
	s_mov_b64 s[98:99], exec
	v_cmp_gt_u32_e32 vcc, 64, v146
	s_and_b64 exec, s[98:99], vcc
	s_add_u32 s60, s22, 0x36e00000
	s_addc_u32 s61, s23, 0
	s_add_u32 s100, s20, 0x18200000
	s_addc_u32 s101, s21, 0
	s_lshl_b32 s56, s14, 15
	s_add_u32 s60, s60, s56
	s_addc_u32 s61, s61, 0
	s_lshl_b32 s56, s14, 16
	s_add_u32 s100, s100, s56
	s_addc_u32 s101, s101, 0
	v_lshlrev_b32_e32 v174, 7, v149
	v_lshl_add_u32 v174, v146, 1, v174
	v_lshlrev_b32_e32 v175, 8, v149
	v_lshl_add_u32 v175, v146, 2, v175
	global_store_dwordx4 v175, v[124:127], s[100:101]
	global_store_dwordx4 v175, v[120:123], s[100:101] offset:16
	v_cvt_pk_bf16_f32 v128, v124, v125
	v_cvt_pk_bf16_f32 v129, v126, v127
	v_cvt_pk_bf16_f32 v130, v120, v121
	v_cvt_pk_bf16_f32 v131, v122, v123
	global_store_dwordx4 v174, v[128:131], s[60:61]
	s_add_u32 s60, s60, 0x800
	s_addc_u32 s61, s61, 0
	s_add_u32 s100, s100, 0x1000
	s_addc_u32 s101, s101, 0
	global_store_dwordx4 v175, v[108:111], s[100:101]
	global_store_dwordx4 v175, v[104:107], s[100:101] offset:16
	v_cvt_pk_bf16_f32 v132, v108, v109
	v_cvt_pk_bf16_f32 v133, v110, v111
	v_cvt_pk_bf16_f32 v134, v104, v105
	v_cvt_pk_bf16_f32 v135, v106, v107
	global_store_dwordx4 v174, v[132:135], s[60:61]
	s_add_u32 s60, s60, 0x800
	s_addc_u32 s61, s61, 0
	s_add_u32 s100, s100, 0x1000
	s_addc_u32 s101, s101, 0
	global_store_dwordx4 v175, v[92:95], s[100:101]
	global_store_dwordx4 v175, v[88:91], s[100:101] offset:16
	v_cvt_pk_bf16_f32 v128, v92, v93
	v_cvt_pk_bf16_f32 v129, v94, v95
	v_cvt_pk_bf16_f32 v130, v88, v89
	v_cvt_pk_bf16_f32 v131, v90, v91
	global_store_dwordx4 v174, v[128:131], s[60:61]
	s_add_u32 s60, s60, 0x800
	s_addc_u32 s61, s61, 0
	s_add_u32 s100, s100, 0x1000
	s_addc_u32 s101, s101, 0
	global_store_dwordx4 v175, v[76:79], s[100:101]
	global_store_dwordx4 v175, v[72:75], s[100:101] offset:16
	v_cvt_pk_bf16_f32 v132, v76, v77
	v_cvt_pk_bf16_f32 v133, v78, v79
	v_cvt_pk_bf16_f32 v134, v72, v73
	v_cvt_pk_bf16_f32 v135, v74, v75
	global_store_dwordx4 v174, v[132:135], s[60:61]
	s_add_u32 s60, s60, 0x2800
	s_addc_u32 s61, s61, 0
	s_add_u32 s100, s100, 0x5000
	s_addc_u32 s101, s101, 0
	global_store_dwordx4 v175, v[60:63], s[100:101]
	global_store_dwordx4 v175, v[56:59], s[100:101] offset:16
	v_cvt_pk_bf16_f32 v128, v60, v61
	v_cvt_pk_bf16_f32 v129, v62, v63
	v_cvt_pk_bf16_f32 v130, v56, v57
	v_cvt_pk_bf16_f32 v131, v58, v59
	global_store_dwordx4 v174, v[128:131], s[60:61]
	s_add_u32 s60, s60, 0x800
	s_addc_u32 s61, s61, 0
	s_add_u32 s100, s100, 0x1000
	s_addc_u32 s101, s101, 0
	global_store_dwordx4 v175, v[44:47], s[100:101]
	global_store_dwordx4 v175, v[40:43], s[100:101] offset:16
	v_cvt_pk_bf16_f32 v132, v44, v45
	v_cvt_pk_bf16_f32 v133, v46, v47
	v_cvt_pk_bf16_f32 v134, v40, v41
	v_cvt_pk_bf16_f32 v135, v42, v43
	global_store_dwordx4 v174, v[132:135], s[60:61]
	s_add_u32 s60, s60, 0x800
	s_addc_u32 s61, s61, 0
	s_add_u32 s100, s100, 0x1000
	s_addc_u32 s101, s101, 0
	global_store_dwordx4 v175, v[28:31], s[100:101]
	global_store_dwordx4 v175, v[24:27], s[100:101] offset:16
	v_cvt_pk_bf16_f32 v128, v28, v29
	v_cvt_pk_bf16_f32 v129, v30, v31
	v_cvt_pk_bf16_f32 v130, v24, v25
	v_cvt_pk_bf16_f32 v131, v26, v27
	global_store_dwordx4 v174, v[128:131], s[60:61]
	s_add_u32 s60, s60, 0x800
	s_addc_u32 s61, s61, 0
	s_add_u32 s100, s100, 0x1000
	s_addc_u32 s101, s101, 0
	global_store_dwordx4 v175, v[12:15], s[100:101]
	global_store_dwordx4 v175, v[8:11], s[100:101] offset:16
	v_cvt_pk_bf16_f32 v132, v12, v13
	v_cvt_pk_bf16_f32 v133, v14, v15
	v_cvt_pk_bf16_f32 v134, v8, v9
	v_cvt_pk_bf16_f32 v135, v10, v11
	global_store_dwordx4 v174, v[132:135], s[60:61]
	s_mov_b64 exec, s[98:99]
	v_cmp_eq_u32_e32 vcc, 64, v146
	s_and_b64 exec, s[98:99], vcc
	s_add_u32 s100, s22, 0x37600000
	s_addc_u32 s101, s23, 0
	s_lshl_b32 s56, s14, 13
	s_add_u32 s100, s100, s56
	s_addc_u32 s101, s101, 0
	v_lshlrev_b32_e32 v175, 5, v149
	global_store_dwordx4 v175, v[124:127], s[100:101]
	global_store_dwordx4 v175, v[120:123], s[100:101] offset:16
	s_add_u32 s100, s100, 0x200
	s_addc_u32 s101, s101, 0
	global_store_dwordx4 v175, v[108:111], s[100:101]
	global_store_dwordx4 v175, v[104:107], s[100:101] offset:16
	s_add_u32 s100, s100, 0x200
	s_addc_u32 s101, s101, 0
	global_store_dwordx4 v175, v[92:95], s[100:101]
	global_store_dwordx4 v175, v[88:91], s[100:101] offset:16
	s_add_u32 s100, s100, 0x200
	s_addc_u32 s101, s101, 0
	global_store_dwordx4 v175, v[76:79], s[100:101]
	global_store_dwordx4 v175, v[72:75], s[100:101] offset:16
	s_add_u32 s100, s100, 0xa00
	s_addc_u32 s101, s101, 0
	global_store_dwordx4 v175, v[60:63], s[100:101]
	global_store_dwordx4 v175, v[56:59], s[100:101] offset:16
	s_add_u32 s100, s100, 0x200
	s_addc_u32 s101, s101, 0
	global_store_dwordx4 v175, v[44:47], s[100:101]
	global_store_dwordx4 v175, v[40:43], s[100:101] offset:16
	s_add_u32 s100, s100, 0x200
	s_addc_u32 s101, s101, 0
	global_store_dwordx4 v175, v[28:31], s[100:101]
	global_store_dwordx4 v175, v[24:27], s[100:101] offset:16
	s_add_u32 s100, s100, 0x200
	s_addc_u32 s101, s101, 0
	global_store_dwordx4 v175, v[12:15], s[100:101]
	global_store_dwordx4 v175, v[8:11], s[100:101] offset:16
	s_mov_b64 exec, s[98:99]
	s_branch .Lwin_done
